# v083 plus L2 warm-up of the next weight-conversion tile (discarded dword loads after the tile's data loads)
# speedup vs baseline: 1.0029x; 1.0005x over previous
; #define GPTR(T, ptr) ((__attribute__((address_space(1))) T*)(ptr))
; __device__ void cvt_tile(const CvtJob& c, int tile, bfu* wt, const int tid_) {
;     ...
;   const float* src = c.src0; int l0;
;   if (c.kind == 0) l0 = n0;
;   else if (c.kind == 1) l0 = (n0 < 2048) ? n0 : n0 + 8;
;   else if (c.kind == 2) {
;     if (n0 < 3072) { int tl = n0 >> 8, w = n0 & 255, bj = w >> 7, hsel = (w & 127) >> 6; l0 = 2048 + tl * 256 + hsel * 128 + bj * 64; }
;     else l0 = 2048 + n0;
;   } else { int tl = n0 >> 8, w = n0 & 255; src = (w < 128) ? c.src0 : c.src1; l0 = tl * 128 + (w & 127); }
;   const int tid = tid_;
;   __syncthreads();
;   { f32x4 v[8];
;     _Pragma("unroll") for (int i = 0; i < 8; ++i) { const int idx = tid + 512 * i; const int kk = idx >> 4, n4 = idx & 15;
;       v[i] = *GPTR(const f32x4, src + (long)(k0 + kk) * c.ld + l0 + n4 * 4); }
;     _Pragma("unroll") for (int i = 0; i < 8; ++i) { const int idx = tid + 512 * i; const int kk = idx >> 4, n4 = idx & 15;
;       const float gsc = c.gain ? c.gain[k0 + kk] : 1.0f;
;       _Pragma("unroll") for (int e = 0; e < 4; ++e) ts[kk * 65 + n4 * 4 + e] = v[i][e] * gsc; } }
.LBB0_329:
	s_ashr_i32 s1, s0, 31
	s_lshl_b64 s[0:1], s[0:1], 2
	v_lshlrev_b32_e32 v0, 2, v53
	v_or_b32_e32 v56, s33, v53
	s_add_u32 s0, s14, s0
	v_and_b32_e32 v64, 60, v0
	s_addc_u32 s1, s15, s1
	v_lshlrev_b32_e32 v0, 2, v64
	v_ashrrev_i32_e32 v65, 4, v56
	s_mul_i32 s14, s26, s93
	s_waitcnt lgkmcnt(0)
	v_lshl_add_u64 v[2:3], s[0:1], 0, v[0:1]
	v_subrev_u32_e32 v0, s14, v65
	v_add_u32_e32 v48, s2, v0
	v_ashrrev_i32_e32 v49, 31, v48
	v_add_u32_e32 v55, 0x200, v56
	v_mul_lo_u32 v0, s36, v49
	v_mul_lo_u32 v6, s37, v48
	v_mad_u64_u32 v[4:5], s[0:1], s36, v48, 0
	v_ashrrev_i32_e32 v63, 4, v55
	v_add3_u32 v5, v5, v0, v6
	v_subrev_u32_e32 v0, s14, v63
	v_add_u32_e32 v46, s2, v0
	v_ashrrev_i32_e32 v47, 31, v46
	v_add_u32_e32 v54, 0x400, v56
	v_mul_lo_u32 v0, s36, v47
	v_mul_lo_u32 v8, s37, v46
	v_mad_u64_u32 v[6:7], s[0:1], s36, v46, 0
	v_ashrrev_i32_e32 v62, 4, v54
	v_add3_u32 v7, v7, v0, v8
	v_subrev_u32_e32 v0, s14, v62
	v_add_u32_e32 v44, s2, v0
	v_lshl_add_u64 v[4:5], v[4:5], 2, v[2:3]
	v_lshl_add_u64 v[6:7], v[6:7], 2, v[2:3]
	v_ashrrev_i32_e32 v45, 31, v44
	v_add_u32_e32 v51, 0x600, v56
	s_barrier
	s_mov_b32 s101, 0x2000
	s_cmp_eq_u32 s39, 3
	s_cselect_b32 s101, 0x1000, s101
	s_cmp_eq_u32 s39, 2
	s_cselect_b32 s101, 0, s101
	s_cmp_eq_u32 s63, 4
	s_cselect_b32 s101, s101, 0
	s_add_i32 s100, s97, s62
	s_cmp_lt_i32 s100, s96
	s_cselect_b32 s100, s101, 0
	s_mov_b32 s101, 0
	v_mov_b32_e32 v66, 1.0
	v_mov_b32_e32 v68, 1.0
	v_mov_b32_e32 v70, 1.0
	v_mov_b32_e32 v72, 1.0
	v_mov_b32_e32 v74, 1.0
	v_mov_b32_e32 v76, 1.0
	v_mov_b32_e32 v78, 1.0
	v_mov_b32_e32 v80, 1.0
	s_andn2_b64 vcc, exec, s[28:29]
	s_cbranch_vccnz .Lcvt_nogain
	v_lshlrev_b32_e32 v82, 2, v48
	global_load_dword v66, v82, s[18:19]
	global_load_dword v68, v82, s[18:19] offset:128
	global_load_dword v70, v82, s[18:19] offset:256
	global_load_dword v72, v82, s[18:19] offset:384
	global_load_dword v74, v82, s[18:19] offset:512
	global_load_dword v76, v82, s[18:19] offset:640
	global_load_dword v78, v82, s[18:19] offset:768
	global_load_dword v80, v82, s[18:19] offset:896
.Lcvt_nogain:
	v_lshl_add_u64 v[142:143], v[4:5], 0, s[100:101]
	global_load_dwordx4 v[30:33], v[4:5], off
	v_lshl_add_u64 v[144:145], v[6:7], 0, s[100:101]
	global_load_dwordx4 v[18:21], v[6:7], off
	v_mul_lo_u32 v0, s36, v45
	v_mul_lo_u32 v6, s37, v44
	v_mad_u64_u32 v[4:5], s[0:1], s36, v44, 0
	v_ashrrev_i32_e32 v61, 4, v51
	v_add3_u32 v5, v5, v0, v6
	v_subrev_u32_e32 v0, s14, v61
	v_add_u32_e32 v42, s2, v0
	v_ashrrev_i32_e32 v43, 31, v42
	v_mul_lo_u32 v0, s36, v43
	v_mul_lo_u32 v8, s37, v42
	v_mad_u64_u32 v[6:7], s[0:1], s36, v42, 0
	v_add3_u32 v7, v7, v0, v8
	v_add_u32_e32 v0, 0x800, v56
	v_ashrrev_i32_e32 v60, 4, v0
	v_subrev_u32_e32 v0, s14, v60
	v_add_u32_e32 v40, s2, v0
	v_lshl_add_u64 v[4:5], v[4:5], 2, v[2:3]
	v_lshl_add_u64 v[6:7], v[6:7], 2, v[2:3]
	v_ashrrev_i32_e32 v41, 31, v40
	v_lshl_add_u64 v[146:147], v[4:5], 0, s[100:101]
	global_load_dwordx4 v[26:29], v[4:5], off
	v_lshl_add_u64 v[148:149], v[6:7], 0, s[100:101]
	global_load_dwordx4 v[10:13], v[6:7], off
	v_mul_lo_u32 v0, s36, v41
	v_mul_lo_u32 v6, s37, v40
	v_mad_u64_u32 v[4:5], s[0:1], s36, v40, 0
	v_add3_u32 v5, v5, v0, v6
	v_add_u32_e32 v0, 0xa00, v56
	v_ashrrev_i32_e32 v59, 4, v0
	v_subrev_u32_e32 v0, s14, v59
	v_add_u32_e32 v38, s2, v0
	v_ashrrev_i32_e32 v39, 31, v38
	v_mul_lo_u32 v0, s36, v39
	v_mul_lo_u32 v8, s37, v38
	v_mad_u64_u32 v[6:7], s[0:1], s36, v38, 0
	v_add3_u32 v7, v7, v0, v8
	v_add_u32_e32 v0, 0xc00, v56
	v_ashrrev_i32_e32 v58, 4, v0
	v_subrev_u32_e32 v0, s14, v58
	v_add_u32_e32 v36, s2, v0
	v_lshl_add_u64 v[4:5], v[4:5], 2, v[2:3]
	v_lshl_add_u64 v[6:7], v[6:7], 2, v[2:3]
	v_ashrrev_i32_e32 v37, 31, v36
	v_lshl_add_u64 v[150:151], v[4:5], 0, s[100:101]
	global_load_dwordx4 v[22:25], v[4:5], off
	s_nop 0
	v_lshl_add_u64 v[152:153], v[6:7], 0, s[100:101]
	global_load_dwordx4 v[6:9], v[6:7], off
	v_mul_lo_u32 v0, s36, v37
	v_mul_lo_u32 v14, s37, v36
	v_mad_u64_u32 v[4:5], s[0:1], s36, v36, 0
	v_add3_u32 v5, v5, v0, v14
	v_add_u32_e32 v0, 0xe00, v56
	v_ashrrev_i32_e32 v57, 4, v0
	v_subrev_u32_e32 v0, s14, v57
	v_add_u32_e32 v34, s2, v0
	v_ashrrev_i32_e32 v35, 31, v34
	v_mul_lo_u32 v0, s36, v35
	v_mul_lo_u32 v16, s37, v34
	v_mad_u64_u32 v[14:15], s[0:1], s36, v34, 0
	v_add3_u32 v15, v15, v0, v16
	v_lshl_add_u64 v[4:5], v[4:5], 2, v[2:3]
	v_lshl_add_u64 v[2:3], v[14:15], 2, v[2:3]
	v_lshl_add_u64 v[154:155], v[4:5], 0, s[100:101]
	global_load_dwordx4 v[14:17], v[4:5], off
	s_nop 0
	v_lshl_add_u64 v[156:157], v[2:3], 0, s[100:101]
	global_load_dwordx4 v[2:5], v[2:3], off
	global_load_dword v160, v[142:143], off
	global_load_dword v160, v[144:145], off
	global_load_dword v160, v[146:147], off
	global_load_dword v160, v[148:149], off
	global_load_dword v160, v[150:151], off
	global_load_dword v160, v[152:153], off
	global_load_dword v160, v[154:155], off
	global_load_dword v160, v[156:157], off
	v_lshl_add_u32 v0, v64, 2, 0
	v_mad_u32_u24 v83, v65, s75, v0
	s_waitcnt vmcnt(15)
	v_pk_mul_f32 v[30:31], v[30:31], v[66:67] op_sel_hi:[1,0]
	v_pk_mul_f32 v[32:33], v[32:33], v[66:67] op_sel_hi:[1,0]
	ds_write2_b32 v83, v30, v31 offset1:1
	ds_write2_b32 v83, v32, v33 offset0:2 offset1:3
	v_mad_u32_u24 v83, v63, s75, v0
	s_waitcnt vmcnt(14)
	v_pk_mul_f32 v[18:19], v[18:19], v[68:69] op_sel_hi:[1,0]
	v_pk_mul_f32 v[20:21], v[20:21], v[68:69] op_sel_hi:[1,0]
	ds_write2_b32 v83, v18, v19 offset1:1
	ds_write2_b32 v83, v20, v21 offset0:2 offset1:3
	v_mad_u32_u24 v83, v62, s75, v0
	s_waitcnt vmcnt(13)
	v_pk_mul_f32 v[26:27], v[26:27], v[70:71] op_sel_hi:[1,0]
	v_pk_mul_f32 v[28:29], v[28:29], v[70:71] op_sel_hi:[1,0]
	ds_write2_b32 v83, v26, v27 offset1:1
	ds_write2_b32 v83, v28, v29 offset0:2 offset1:3
	v_mad_u32_u24 v83, v61, s75, v0
	s_waitcnt vmcnt(12)
	v_pk_mul_f32 v[10:11], v[10:11], v[72:73] op_sel_hi:[1,0]
	v_pk_mul_f32 v[12:13], v[12:13], v[72:73] op_sel_hi:[1,0]
	ds_write2_b32 v83, v10, v11 offset1:1
	ds_write2_b32 v83, v12, v13 offset0:2 offset1:3
	v_mad_u32_u24 v83, v60, s75, v0
	s_waitcnt vmcnt(11)
	v_pk_mul_f32 v[22:23], v[22:23], v[74:75] op_sel_hi:[1,0]
	v_pk_mul_f32 v[24:25], v[24:25], v[74:75] op_sel_hi:[1,0]
	ds_write2_b32 v83, v22, v23 offset1:1
	ds_write2_b32 v83, v24, v25 offset0:2 offset1:3
	v_mad_u32_u24 v83, v59, s75, v0
	s_waitcnt vmcnt(10)
	v_pk_mul_f32 v[6:7], v[6:7], v[76:77] op_sel_hi:[1,0]
	v_pk_mul_f32 v[8:9], v[8:9], v[76:77] op_sel_hi:[1,0]
	ds_write2_b32 v83, v6, v7 offset1:1
	ds_write2_b32 v83, v8, v9 offset0:2 offset1:3
	v_mad_u32_u24 v83, v58, s75, v0
	s_waitcnt vmcnt(9)
	v_pk_mul_f32 v[14:15], v[14:15], v[78:79] op_sel_hi:[1,0]
	v_pk_mul_f32 v[16:17], v[16:17], v[78:79] op_sel_hi:[1,0]
	ds_write2_b32 v83, v14, v15 offset1:1
	ds_write2_b32 v83, v16, v17 offset0:2 offset1:3
	v_mad_u32_u24 v83, v57, s75, v0
	s_waitcnt vmcnt(8)
	v_pk_mul_f32 v[2:3], v[2:3], v[80:81] op_sel_hi:[1,0]
	v_pk_mul_f32 v[4:5], v[4:5], v[80:81] op_sel_hi:[1,0]
	ds_write2_b32 v83, v2, v3 offset1:1
	ds_write2_b32 v83, v4, v5 offset0:2 offset1:3
	s_branch .Lcvt_tail

; __global__ void __launch_bounds__(NTHR, 2) fwd_megakernel(Params p) {
	.amdhsa_kernel _Z14fwd_megakernel6Params
		.amdhsa_group_segment_fixed_size 0
		.amdhsa_private_segment_fixed_size 0
		.amdhsa_kernarg_size 432
		.amdhsa_user_sgpr_count 2
		.amdhsa_user_sgpr_dispatch_ptr 0
		.amdhsa_user_sgpr_queue_ptr 0
		.amdhsa_user_sgpr_kernarg_segment_ptr 1
		.amdhsa_user_sgpr_dispatch_id 0
		.amdhsa_user_sgpr_kernarg_preload_length 0
		.amdhsa_user_sgpr_kernarg_preload_offset 0
		.amdhsa_user_sgpr_private_segment_size 0
		.amdhsa_uses_dynamic_stack 0
		.amdhsa_enable_private_segment 0
		.amdhsa_system_sgpr_workgroup_id_x 1
		.amdhsa_system_sgpr_workgroup_id_y 0
		.amdhsa_system_sgpr_workgroup_id_z 0
		.amdhsa_system_sgpr_workgroup_info 0
		.amdhsa_system_vgpr_workitem_id 2
		.amdhsa_next_free_vgpr 256
		.amdhsa_next_free_sgpr 102
		.amdhsa_accum_offset 256
		.amdhsa_reserve_vcc 1
		.amdhsa_float_round_mode_32 0
		.amdhsa_float_round_mode_16_64 0
		.amdhsa_float_denorm_mode_32 3
		.amdhsa_float_denorm_mode_16_64 3
		.amdhsa_dx10_clamp 1
		.amdhsa_ieee_mode 1
		.amdhsa_fp16_overflow 0
		.amdhsa_tg_split 0
		.amdhsa_exception_fp_ieee_invalid_op 0
		.amdhsa_exception_fp_denorm_src 0
		.amdhsa_exception_fp_ieee_div_zero 0
		.amdhsa_exception_fp_ieee_overflow 0
		.amdhsa_exception_fp_ieee_underflow 0
		.amdhsa_exception_fp_ieee_inexact 0
		.amdhsa_exception_int_div_zero 0
	.end_amdhsa_kernel

; __global__ void __launch_bounds__(NTHR, 2) fwd_megakernel(Params p) {
amdhsa.kernels:
  - .agpr_count:     0
    .args:
      - .offset:         0
        .size:           176
        .value_kind:     by_value
      - .offset:         176
        .size:           4
        .value_kind:     hidden_block_count_x
      - .offset:         180
        .size:           4
        .value_kind:     hidden_block_count_y
      - .offset:         184
        .size:           4
        .value_kind:     hidden_block_count_z
      - .offset:         188
        .size:           2
        .value_kind:     hidden_group_size_x
      - .offset:         190
        .size:           2
        .value_kind:     hidden_group_size_y
      - .offset:         192
        .size:           2
        .value_kind:     hidden_group_size_z
      - .offset:         194
        .size:           2
        .value_kind:     hidden_remainder_x
      - .offset:         196
        .size:           2
        .value_kind:     hidden_remainder_y
      - .offset:         198
        .size:           2
        .value_kind:     hidden_remainder_z
      - .offset:         216
        .size:           8
        .value_kind:     hidden_global_offset_x
      - .offset:         224
        .size:           8
        .value_kind:     hidden_global_offset_y
      - .offset:         232
        .size:           8
        .value_kind:     hidden_global_offset_z
      - .offset:         240
        .size:           2
        .value_kind:     hidden_grid_dims
      - .offset:         264
        .size:           8
        .value_kind:     hidden_multigrid_sync_arg
      - .offset:         296
        .size:           4
        .value_kind:     hidden_dynamic_lds_size
    .group_segment_fixed_size: 0
    .kernarg_segment_align: 8
    .kernarg_segment_size: 432
    .language:       OpenCL C
    .language_version:
      - 2
      - 0
    .max_flat_workgroup_size: 512
    .name:           _Z14fwd_megakernel6Params
    .private_segment_fixed_size: 0
    .sgpr_count:     108
    .sgpr_spill_count: 227
    .symbol:         _Z14fwd_megakernel6Params.kd
    .uniform_work_group_size: 1
    .uses_dynamic_stack: false
    .vgpr_count:     256
    .vgpr_spill_count: 0
    .wavefront_size: 64
